# LRU pass-2: the 16 second-round context tiles are spread two per XCD instead of all on XCD 0
# speedup vs baseline: 1.0023x; 1.0023x over previous
.LBB0_290:
	v_add_u32_e32 v5, s6, v0
	ds_read2st64_b32 v[8:9], v5 offset1:1
	ds_read2st64_b32 v[12:13], v6 offset1:1
	ds_read2st64_b32 v[14:15], v6 offset0:2 offset1:3
	s_add_i32 s6, s6, 64
	s_cmpk_lg_i32 s6, 0x100
	s_waitcnt lgkmcnt(2)
	v_add_f32_e32 v7, 0, v8
	v_add_f32_e32 v7, v7, v9
	ds_read2st64_b32 v[8:9], v5 offset0:2 offset1:3
	s_waitcnt lgkmcnt(0)
	v_add_f32_e32 v7, v7, v8
	v_add_f32_e32 v7, v7, v9
	ds_read2st64_b32 v[8:9], v5 offset0:4 offset1:5
	s_waitcnt lgkmcnt(0)
	v_add_f32_e32 v7, v7, v8
	v_add_f32_e32 v7, v7, v9
	ds_read2st64_b32 v[8:9], v5 offset0:6 offset1:7
	s_waitcnt lgkmcnt(0)
	v_add_f32_e32 v5, v7, v8
	v_add_f32_e32 v5, v5, v9
	v_fmamk_f32 v5, v5, 0x3b000000, v190
	v_cmp_gt_f32_e32 vcc, s96, v5
	v_mul_f32_e32 v7, 0x4b800000, v5
	s_nop 0
	v_cndmask_b32_e32 v5, v5, v7, vcc
	v_rsq_f32_e32 v5, v5
	s_nop 0
	v_mul_f32_e32 v7, 0x45800000, v5
	v_cndmask_b32_e32 v8, v5, v7, vcc
	v_ashrrev_i32_e32 v5, 31, v4
	v_lshlrev_b64 v[10:11], 11, v[4:5]
	v_pk_mul_f32 v[12:13], v[12:13], v[8:9] op_sel_hi:[1,0]
	v_pk_mul_f32 v[14:15], v[14:15], v[8:9] op_sel_hi:[1,0]
	v_lshl_add_u64 v[10:11], v[2:3], 0, v[10:11]
	v_cvt_pk_bf16_f32 v12, v12, v13
	v_cvt_pk_bf16_f32 v13, v14, v15
	global_store_dwordx2 v[10:11], v[12:13], off offset:1024
	ds_read2st64_b32 v[12:13], v6 offset0:4 offset1:5
	ds_read2st64_b32 v[14:15], v6 offset0:6 offset1:7
	v_add_u32_e32 v4, 16, v4
	s_waitcnt lgkmcnt(1)
	v_pk_mul_f32 v[12:13], v[12:13], v[8:9] op_sel_hi:[1,0]
	s_waitcnt lgkmcnt(0)
	v_pk_mul_f32 v[14:15], v[8:9], v[14:15] op_sel_hi:[0,1]
	v_cvt_pk_bf16_f32 v12, v12, v13
	v_cvt_pk_bf16_f32 v13, v14, v15
	global_store_dwordx2 v[10:11], v[12:13], off offset:1056
	ds_read2st64_b32 v[12:13], v6 offset0:8 offset1:9
	ds_read2st64_b32 v[14:15], v6 offset0:10 offset1:11
	s_waitcnt lgkmcnt(1)
	v_pk_mul_f32 v[12:13], v[8:9], v[12:13] op_sel_hi:[0,1]
	s_waitcnt lgkmcnt(0)
	v_pk_mul_f32 v[14:15], v[8:9], v[14:15] op_sel_hi:[0,1]
	v_cvt_pk_bf16_f32 v12, v12, v13
	v_cvt_pk_bf16_f32 v13, v14, v15
	global_store_dwordx2 v[10:11], v[12:13], off offset:1088
	ds_read2st64_b32 v[12:13], v6 offset0:12 offset1:13
	ds_read2st64_b32 v[14:15], v6 offset0:14 offset1:15
	v_add_u32_e32 v6, 0x1000, v6
	s_waitcnt lgkmcnt(1)
	v_pk_mul_f32 v[12:13], v[8:9], v[12:13] op_sel_hi:[0,1]
	s_waitcnt lgkmcnt(0)
	v_pk_mul_f32 v[8:9], v[8:9], v[14:15] op_sel_hi:[0,1]
	v_cvt_pk_bf16_f32 v12, v12, v13
	v_cvt_pk_bf16_f32 v13, v8, v9
	global_store_dwordx2 v[10:11], v[12:13], off offset:1120
	s_cbranch_scc1 .LBB0_290
	s_add_i32 s6, s10, s43
	s_ashr_i32 s7, s6, 31
	v_lshrrev_b32_e32 v2, 4, v228
	v_and_b32_e32 v3, 15, v228
	v_lshlrev_b32_e32 v3, 4, v3
	s_lshl_b64 s[6:7], s[6:7], 11
	v_lshl_add_u32 v5, v2, 11, v3
	s_add_u32 s6, s33, s6
	s_addc_u32 s7, s42, s7
	v_add_u32_e32 v7, 0x2000, v5
	s_mov_b32 s10, 0xffff0000
	s_waitcnt vmcnt(20)
	v_lshlrev_b32_e32 v40, 16, v130
	v_lshlrev_b32_e32 v41, 16, v131
	v_lshlrev_b32_e32 v42, 16, v132
	v_lshlrev_b32_e32 v43, 16, v133
	v_lshlrev_b32_e32 v44, 16, v134
	v_lshlrev_b32_e32 v45, 16, v135
	v_lshlrev_b32_e32 v46, 16, v136
	v_lshlrev_b32_e32 v47, 16, v137
	v_lshlrev_b32_e32 v48, 16, v138
	v_lshlrev_b32_e32 v49, 16, v139
	v_lshlrev_b32_e32 v50, 16, v140
	v_lshlrev_b32_e32 v51, 16, v141
	v_lshlrev_b32_e32 v52, 16, v142
	v_lshlrev_b32_e32 v53, 16, v143
	v_lshlrev_b32_e32 v54, 16, v144
	v_lshlrev_b32_e32 v55, 16, v145
	v_and_b32_e32 v130, s10, v130
	v_and_b32_e32 v131, s10, v131
	v_and_b32_e32 v132, s10, v132
	v_and_b32_e32 v133, s10, v133
	v_and_b32_e32 v134, s10, v134
	v_and_b32_e32 v135, s10, v135
	v_and_b32_e32 v136, s10, v136
	v_and_b32_e32 v137, s10, v137
	v_and_b32_e32 v138, s10, v138
	v_and_b32_e32 v139, s10, v139
	v_and_b32_e32 v140, s10, v140
	v_and_b32_e32 v141, s10, v141
	v_and_b32_e32 v142, s10, v142
	v_and_b32_e32 v143, s10, v143
	v_and_b32_e32 v144, s10, v144
	v_and_b32_e32 v145, s10, v145
	v_mul_f32_e32 v72, v40, v40
	v_mul_f32_e32 v73, v41, v41
	v_mul_f32_e32 v74, v42, v42
	v_mul_f32_e32 v75, v43, v43
	v_fmac_f32_e32 v72, v130, v130
	v_fmac_f32_e32 v73, v131, v131
	v_fmac_f32_e32 v74, v132, v132
	v_fmac_f32_e32 v75, v133, v133
	v_fmac_f32_e32 v72, v44, v44
	v_fmac_f32_e32 v73, v45, v45
	v_fmac_f32_e32 v74, v46, v46
	v_fmac_f32_e32 v75, v47, v47
	v_fmac_f32_e32 v72, v48, v48
	v_fmac_f32_e32 v73, v49, v49
	v_fmac_f32_e32 v74, v50, v50
	v_fmac_f32_e32 v75, v51, v51
	v_fmac_f32_e32 v72, v52, v52
	v_fmac_f32_e32 v73, v53, v53
	v_fmac_f32_e32 v74, v54, v54
	v_fmac_f32_e32 v75, v55, v55
	v_fmac_f32_e32 v72, v134, v134
	v_fmac_f32_e32 v73, v135, v135
	v_fmac_f32_e32 v74, v136, v136
	v_fmac_f32_e32 v75, v137, v137
	v_fmac_f32_e32 v72, v138, v138
	v_fmac_f32_e32 v73, v139, v139
	v_fmac_f32_e32 v74, v140, v140
	v_fmac_f32_e32 v75, v141, v141
	v_fmac_f32_e32 v72, v142, v142
	v_fmac_f32_e32 v73, v143, v143
	v_fmac_f32_e32 v74, v144, v144
	v_fmac_f32_e32 v75, v145, v145
	v_add_f32_e32 v72, v72, v73
	v_add_f32_e32 v74, v74, v75
	s_nop 0
	v_add_f32_e32 v72, v72, v74
	s_waitcnt vmcnt(16)
	v_lshlrev_b32_e32 v56, 16, v146
	v_lshlrev_b32_e32 v57, 16, v147
	v_lshlrev_b32_e32 v58, 16, v148
	v_lshlrev_b32_e32 v59, 16, v149
	v_lshlrev_b32_e32 v60, 16, v150
	v_lshlrev_b32_e32 v61, 16, v151
	v_lshlrev_b32_e32 v62, 16, v152
	v_lshlrev_b32_e32 v63, 16, v153
	v_lshlrev_b32_e32 v64, 16, v154
	v_lshlrev_b32_e32 v65, 16, v155
	v_lshlrev_b32_e32 v66, 16, v156
	v_lshlrev_b32_e32 v67, 16, v157
	v_lshlrev_b32_e32 v68, 16, v158
	v_lshlrev_b32_e32 v69, 16, v159
	v_lshlrev_b32_e32 v70, 16, v160
	v_lshlrev_b32_e32 v71, 16, v161
	v_and_b32_e32 v146, s10, v146
	v_and_b32_e32 v147, s10, v147
	v_and_b32_e32 v148, s10, v148
	v_and_b32_e32 v149, s10, v149
	v_and_b32_e32 v150, s10, v150
	v_and_b32_e32 v151, s10, v151
	v_and_b32_e32 v152, s10, v152
	v_and_b32_e32 v153, s10, v153
	v_and_b32_e32 v154, s10, v154
	v_and_b32_e32 v155, s10, v155
	v_and_b32_e32 v156, s10, v156
	v_and_b32_e32 v157, s10, v157
	v_and_b32_e32 v158, s10, v158
	v_and_b32_e32 v159, s10, v159
	v_and_b32_e32 v160, s10, v160
	v_and_b32_e32 v161, s10, v161
	v_mul_f32_e32 v76, v56, v56
	v_mul_f32_e32 v77, v57, v57
	v_mul_f32_e32 v78, v58, v58
	v_mul_f32_e32 v79, v59, v59
	v_fmac_f32_e32 v76, v146, v146
	v_fmac_f32_e32 v77, v147, v147
	v_fmac_f32_e32 v78, v148, v148
	v_fmac_f32_e32 v79, v149, v149
	v_fmac_f32_e32 v76, v60, v60
	v_fmac_f32_e32 v77, v61, v61
	v_fmac_f32_e32 v78, v62, v62
	v_fmac_f32_e32 v79, v63, v63
	v_fmac_f32_e32 v76, v64, v64
	v_fmac_f32_e32 v77, v65, v65
	v_fmac_f32_e32 v78, v66, v66
	v_fmac_f32_e32 v79, v67, v67
	v_fmac_f32_e32 v76, v68, v68
	v_fmac_f32_e32 v77, v69, v69
	v_fmac_f32_e32 v78, v70, v70
	v_fmac_f32_e32 v79, v71, v71
	v_fmac_f32_e32 v76, v150, v150
	v_fmac_f32_e32 v77, v151, v151
	v_fmac_f32_e32 v78, v152, v152
	v_fmac_f32_e32 v79, v153, v153
	v_fmac_f32_e32 v76, v154, v154
	v_fmac_f32_e32 v77, v155, v155
	v_fmac_f32_e32 v78, v156, v156
	v_fmac_f32_e32 v79, v157, v157
	v_fmac_f32_e32 v76, v158, v158
	v_fmac_f32_e32 v77, v159, v159
	v_fmac_f32_e32 v78, v160, v160
	v_fmac_f32_e32 v79, v161, v161
	v_add_f32_e32 v76, v76, v77
	v_add_f32_e32 v78, v78, v79
	s_nop 0
	v_add_f32_e32 v76, v76, v78
	s_nop 1
	v_add_f32_dpp v73, v72, v72 quad_perm:[1,0,3,2] row_mask:0xf bank_mask:0xf
	v_add_f32_dpp v77, v76, v76 quad_perm:[1,0,3,2] row_mask:0xf bank_mask:0xf
	s_nop 0
	v_add_f32_dpp v72, v73, v73 quad_perm:[2,3,0,1] row_mask:0xf bank_mask:0xf
	v_add_f32_dpp v76, v77, v77 quad_perm:[2,3,0,1] row_mask:0xf bank_mask:0xf
	s_nop 0
	v_add_f32_dpp v73, v72, v72 row_half_mirror row_mask:0xf bank_mask:0xf
	v_add_f32_dpp v77, v76, v76 row_half_mirror row_mask:0xf bank_mask:0xf
	s_nop 0
	v_add_f32_dpp v72, v73, v73 row_mirror row_mask:0xf bank_mask:0xf
	v_add_f32_dpp v76, v77, v77 row_mirror row_mask:0xf bank_mask:0xf
	s_nop 0
	v_fmamk_f32 v72, v72, 0x3b000000, v190
	v_fmamk_f32 v76, v76, 0x3b000000, v190
	v_cmp_gt_f32_e32 vcc, s96, v72
	v_cmp_gt_f32_e64 s[8:9], s96, v76
	v_mul_f32_e32 v73, 0x4b800000, v72
	v_mul_f32_e32 v77, 0x4b800000, v76
	v_cndmask_b32_e32 v72, v72, v73, vcc
	v_cndmask_b32_e64 v76, v76, v77, s[8:9]
	v_rsq_f32_e32 v72, v72
	v_rsq_f32_e32 v76, v76
	s_nop 0
	v_mul_f32_e32 v73, 0x45800000, v72
	v_mul_f32_e32 v77, 0x45800000, v76
	v_cndmask_b32_e32 v72, v72, v73, vcc
	v_cndmask_b32_e64 v76, v76, v77, s[8:9]
	v_mul_f32_e32 v40, v72, v40
	v_mul_f32_e32 v41, v72, v41
	v_mul_f32_e32 v42, v72, v42
	v_mul_f32_e32 v43, v72, v43
	v_mul_f32_e32 v44, v72, v44
	v_mul_f32_e32 v45, v72, v45
	v_mul_f32_e32 v46, v72, v46
	v_mul_f32_e32 v47, v72, v47
	v_mul_f32_e32 v48, v72, v48
	v_mul_f32_e32 v49, v72, v49
	v_mul_f32_e32 v50, v72, v50
	v_mul_f32_e32 v51, v72, v51
	v_mul_f32_e32 v52, v72, v52
	v_mul_f32_e32 v53, v72, v53
	v_mul_f32_e32 v54, v72, v54
	v_mul_f32_e32 v55, v72, v55
	v_mul_f32_e32 v130, v72, v130
	v_mul_f32_e32 v131, v72, v131
	v_mul_f32_e32 v132, v72, v132
	v_mul_f32_e32 v133, v72, v133
	v_mul_f32_e32 v134, v72, v134
	v_mul_f32_e32 v135, v72, v135
	v_mul_f32_e32 v136, v72, v136
	v_mul_f32_e32 v137, v72, v137
	v_mul_f32_e32 v138, v72, v138
	v_mul_f32_e32 v139, v72, v139
	v_mul_f32_e32 v140, v72, v140
	v_mul_f32_e32 v141, v72, v141
	v_mul_f32_e32 v142, v72, v142
	v_mul_f32_e32 v143, v72, v143
	v_mul_f32_e32 v144, v72, v144
	v_mul_f32_e32 v145, v72, v145
	v_cvt_pk_bf16_f32 v130, v40, v130
	v_cvt_pk_bf16_f32 v131, v41, v131
	v_cvt_pk_bf16_f32 v132, v42, v132
	v_cvt_pk_bf16_f32 v133, v43, v133
	v_cvt_pk_bf16_f32 v134, v44, v134
	v_cvt_pk_bf16_f32 v135, v45, v135
	v_cvt_pk_bf16_f32 v136, v46, v136
	v_cvt_pk_bf16_f32 v137, v47, v137
	v_cvt_pk_bf16_f32 v138, v48, v138
	v_cvt_pk_bf16_f32 v139, v49, v139
	v_cvt_pk_bf16_f32 v140, v50, v140
	v_cvt_pk_bf16_f32 v141, v51, v141
	v_cvt_pk_bf16_f32 v142, v52, v142
	v_cvt_pk_bf16_f32 v143, v53, v143
	v_cvt_pk_bf16_f32 v144, v54, v144
	v_cvt_pk_bf16_f32 v145, v55, v145
	v_mul_f32_e32 v56, v76, v56
	v_mul_f32_e32 v57, v76, v57
	v_mul_f32_e32 v58, v76, v58
	v_mul_f32_e32 v59, v76, v59
	v_mul_f32_e32 v60, v76, v60
	v_mul_f32_e32 v61, v76, v61
	v_mul_f32_e32 v62, v76, v62
	v_mul_f32_e32 v63, v76, v63
	v_mul_f32_e32 v64, v76, v64
	v_mul_f32_e32 v65, v76, v65
	v_mul_f32_e32 v66, v76, v66
	v_mul_f32_e32 v67, v76, v67
	v_mul_f32_e32 v68, v76, v68
	v_mul_f32_e32 v69, v76, v69
	v_mul_f32_e32 v70, v76, v70
	v_mul_f32_e32 v71, v76, v71
	v_mul_f32_e32 v146, v76, v146
	v_mul_f32_e32 v147, v76, v147
	v_mul_f32_e32 v148, v76, v148
	v_mul_f32_e32 v149, v76, v149
	v_mul_f32_e32 v150, v76, v150
	v_mul_f32_e32 v151, v76, v151
	v_mul_f32_e32 v152, v76, v152
	v_mul_f32_e32 v153, v76, v153
	v_mul_f32_e32 v154, v76, v154
	v_mul_f32_e32 v155, v76, v155
	v_mul_f32_e32 v156, v76, v156
	v_mul_f32_e32 v157, v76, v157
	v_mul_f32_e32 v158, v76, v158
	v_mul_f32_e32 v159, v76, v159
	v_mul_f32_e32 v160, v76, v160
	v_mul_f32_e32 v161, v76, v161
	v_cvt_pk_bf16_f32 v146, v56, v146
	v_cvt_pk_bf16_f32 v147, v57, v147
	v_cvt_pk_bf16_f32 v148, v58, v148
	v_cvt_pk_bf16_f32 v149, v59, v149
	v_cvt_pk_bf16_f32 v150, v60, v150
	v_cvt_pk_bf16_f32 v151, v61, v151
	v_cvt_pk_bf16_f32 v152, v62, v152
	v_cvt_pk_bf16_f32 v153, v63, v153
	v_cvt_pk_bf16_f32 v154, v64, v154
	v_cvt_pk_bf16_f32 v155, v65, v155
	v_cvt_pk_bf16_f32 v156, v66, v156
	v_cvt_pk_bf16_f32 v157, v67, v157
	v_cvt_pk_bf16_f32 v158, v68, v158
	v_cvt_pk_bf16_f32 v159, v69, v159
	v_cvt_pk_bf16_f32 v160, v70, v160
	v_cvt_pk_bf16_f32 v161, v71, v161
	global_store_dwordx4 v5, v[130:133], s[6:7]
	global_store_dwordx4 v5, v[134:137], s[6:7] offset:256
	global_store_dwordx4 v5, v[138:141], s[6:7] offset:512
	global_store_dwordx4 v5, v[142:145], s[6:7] offset:768
	global_store_dwordx4 v7, v[146:149], s[6:7]
	global_store_dwordx4 v7, v[150:153], s[6:7] offset:256
	global_store_dwordx4 v7, v[154:157], s[6:7] offset:512
	global_store_dwordx4 v7, v[158:161], s[6:7] offset:768
	s_waitcnt lgkmcnt(0)
	v_readlane_b32 s6, v255, 31
	s_cmp_lg_u32 s81, 0x100
	s_cbranch_scc1 .Ll2_lat_orig
	s_cmp_lg_u32 s6, 0x110
	s_cbranch_scc1 .Ll2_lat_orig
	s_cmp_ge_i32 s57, 0x100
	s_cbranch_scc1 .Ll2_lat_exit
	s_and_b32 s7, s57, 31
	s_cmp_lt_u32 s7, 2
	s_cbranch_scc0 .Ll2_lat_exit
	s_lshr_b32 s57, s57, 5
	s_lshl_b32 s57, s57, 1
	s_add_i32 s57, s57, s7
	s_addk_i32 s57, 0x100
	s_barrier
	s_branch .LBB0_268
.Ll2_lat_exit:
	s_barrier
	s_branch .LBB0_294
.Ll2_lat_orig:
	s_add_i32 s57, s57, s81
	s_cmp_ge_i32 s57, s6
	s_barrier
	s_cbranch_scc0 .LBB0_268
